# K-loops: static s_setprio 1 for the trailing half during the K-loop only, no per-segment flips
# speedup vs baseline: 1.0045x; 1.0045x over previous
; template <class Epi, class Sched, bool ALIGN_EPI = false, bool SP2 = false>
; __device__ __forceinline__ void gemm_phase(PG8_LAS unsigned char* lds, const Gemm g, const Sched& S, const Epi& E, const int wid_) {
;     ...
; #pragma unroll
;     for (int a = 0; a < 2; ++a)
; #pragma unroll
;         for (int b = 0; b < 2; ++b)
; #pragma unroll
;             for (int m = 0; m < 4; ++m)
; #pragma unroll
;                 for (int n = 0; n < 2; ++n) acc[a][b][m][n] = (f32x4){0.f, 0.f, 0.f, 0.f};
;     bf16x8 At[4][2], B0[2][2], B1[2][2];
;     const char* cA = (const char*)g.A + (size_t)cur.pm * tstepA; const char* cB = (const char*)g.Bt + (size_t)cur.pn * tstepB;
;     S.a_ready(cur);
;     if constexpr (SP2) {
;         PG8_STAGE(PG8_SB(0, 0), cB, voffB); PG8_STAGE(PG8_SB(0, 1), cB + hstepB, voffB); PG8_STAGE(PG8_SA(0, 0), cA, voffA); PG8_STAGE(PG8_SA(0, 1), cA + hstepA, voffA);
;         if (wr == 1) PG8_BAR;
;         PG8_WAIT_V(2); PG8_BAR;
;         PG8_STAGE(PG8_SB(1, 0), cB + kstep, voffB); PG8_STAGE(PG8_SA(1, 0), cA + kstep, voffA); PG8_STAGE(PG8_SB(1, 1), cB + hstepB + kstep, voffB);
;         PG8_WAIT_V(6); PG8_BAR;
;     } else {
;         PG8_STAGE(PG8_SB(0, 0), cB, voffB); PG8_STAGE(PG8_SA(0, 0), cA, voffA); PG8_STAGE(PG8_SB(0, 1), cB + hstepB, voffB); PG8_STAGE(PG8_SA(0, 1), cA + hstepA, voffA);
;         if (wr == 1) PG8_BAR;
;         PG8_WAIT_V(4); PG8_BAR;
;         PG8_STAGE(PG8_SB(1, 0), cB + kstep, voffB); PG8_STAGE(PG8_SA(1, 0), cA + kstep, voffA); PG8_STAGE(PG8_SB(1, 1), cB + hstepB + kstep, voffB);
;         PG8_WAIT_V(6); PG8_BAR;
;     }
;     for (;;) {
;         const bool has_next = S.next(ui + 1, nxt);
;         const char* nA = has_next ? (const char*)g.A + (size_t)nxt.pm * tstepA : cA; const char* nB = has_next ? (const char*)g.Bt + (size_t)nxt.pn * tstepB : cB;
;         for (int t = 0; t < nt; t += 2) {
;             const bool last = (t == nt - 2);
;             const char* a1 = cA + (size_t)(t + 1) * kstep;
;             const char* a2 = last ? nA : cA + (size_t)(t + 2) * kstep; const char* b2 = last ? nB : cB + (size_t)(t + 2) * kstep;
;             const char* a3 = a2 + kstep; const char* b3 = b2 + kstep;
;             if (last && has_next) S.a_ready(nxt);
;             if constexpr (SP2) {
;             PG8_LDB(B0, 0, 0); PG8_LDB(B1, 0, 1); PG8_SCHED; PG8_LDA(At, 0, 0); PG8_STAGE(PG8_SA(1, 1), a1 + hstepA, voffA);
.LBB0_379:
	s_add_u32 s49, s38, 0x100
	s_addc_u32 s62, s39, 0
	s_add_u32 s6, s98, 0x80
	v_mov_b32_e32 v0, 0
	s_addc_u32 s7, s99, 0
	s_mov_b32 s38, 0
	v_mov_b32_e32 v1, v0
	v_mov_b32_e32 v2, v0
	v_mov_b32_e32 v3, v0
	v_mov_b32_e32 v4, v0
	v_mov_b32_e32 v5, v0
	v_mov_b32_e32 v6, v0
	v_mov_b32_e32 v7, v0
	v_mov_b32_e32 v8, v0
	v_mov_b32_e32 v9, v0
	v_mov_b32_e32 v10, v0
	v_mov_b32_e32 v11, v0
	v_mov_b32_e32 v12, v0
	v_mov_b32_e32 v13, v0
	v_mov_b32_e32 v14, v0
	v_mov_b32_e32 v15, v0
	v_mov_b32_e32 v24, v0
	v_mov_b32_e32 v25, v0
	v_mov_b32_e32 v26, v0
	v_mov_b32_e32 v27, v0
	v_mov_b32_e32 v28, v0
	v_mov_b32_e32 v29, v0
	v_mov_b32_e32 v30, v0
	v_mov_b32_e32 v31, v0
	v_mov_b32_e32 v40, v0
	v_mov_b32_e32 v41, v0
	v_mov_b32_e32 v42, v0
	v_mov_b32_e32 v43, v0
	v_mov_b32_e32 v44, v0
	v_mov_b32_e32 v45, v0
	v_mov_b32_e32 v46, v0
	v_mov_b32_e32 v47, v0
	v_mov_b32_e32 v16, v0
	v_mov_b32_e32 v17, v0
	v_mov_b32_e32 v18, v0
	v_mov_b32_e32 v19, v0
	v_mov_b32_e32 v20, v0
	v_mov_b32_e32 v21, v0
	v_mov_b32_e32 v22, v0
	v_mov_b32_e32 v23, v0
	v_mov_b32_e32 v32, v0
	v_mov_b32_e32 v33, v0
	v_mov_b32_e32 v34, v0
	v_mov_b32_e32 v35, v0
	v_mov_b32_e32 v36, v0
	v_mov_b32_e32 v37, v0
	v_mov_b32_e32 v38, v0
	v_mov_b32_e32 v39, v0
	v_mov_b32_e32 v48, v0
	v_mov_b32_e32 v49, v0
	v_mov_b32_e32 v50, v0
	v_mov_b32_e32 v51, v0
	v_mov_b32_e32 v52, v0
	v_mov_b32_e32 v53, v0
	v_mov_b32_e32 v54, v0
	v_mov_b32_e32 v55, v0
	v_mov_b32_e32 v56, v0
	v_mov_b32_e32 v57, v0
	v_mov_b32_e32 v58, v0
	v_mov_b32_e32 v59, v0
	v_mov_b32_e32 v60, v0
	v_mov_b32_e32 v61, v0
	v_mov_b32_e32 v62, v0
	v_mov_b32_e32 v63, v0
	v_mov_b32_e32 v64, v0
	v_mov_b32_e32 v65, v0
	v_mov_b32_e32 v66, v0
	v_mov_b32_e32 v67, v0
	v_mov_b32_e32 v68, v0
	v_mov_b32_e32 v69, v0
	v_mov_b32_e32 v70, v0
	v_mov_b32_e32 v71, v0
	v_mov_b32_e32 v72, v0
	v_mov_b32_e32 v73, v0
	v_mov_b32_e32 v74, v0
	v_mov_b32_e32 v75, v0
	v_mov_b32_e32 v76, v0
	v_mov_b32_e32 v77, v0
	v_mov_b32_e32 v78, v0
	v_mov_b32_e32 v79, v0
	v_mov_b32_e32 v88, v0
	v_mov_b32_e32 v89, v0
	v_mov_b32_e32 v90, v0
	v_mov_b32_e32 v91, v0
	v_mov_b32_e32 v92, v0
	v_mov_b32_e32 v93, v0
	v_mov_b32_e32 v94, v0
	v_mov_b32_e32 v95, v0
	v_mov_b32_e32 v104, v0
	v_mov_b32_e32 v105, v0
	v_mov_b32_e32 v106, v0
	v_mov_b32_e32 v107, v0
	v_mov_b32_e32 v108, v0
	v_mov_b32_e32 v109, v0
	v_mov_b32_e32 v110, v0
	v_mov_b32_e32 v111, v0
	v_mov_b32_e32 v80, v0
	v_mov_b32_e32 v81, v0
	v_mov_b32_e32 v82, v0
	v_mov_b32_e32 v83, v0
	v_mov_b32_e32 v84, v0
	v_mov_b32_e32 v85, v0
	v_mov_b32_e32 v86, v0
	v_mov_b32_e32 v87, v0
	v_mov_b32_e32 v96, v0
	v_mov_b32_e32 v97, v0
	v_mov_b32_e32 v98, v0
	v_mov_b32_e32 v99, v0
	v_mov_b32_e32 v100, v0
	v_mov_b32_e32 v101, v0
	v_mov_b32_e32 v102, v0
	v_mov_b32_e32 v103, v0
	v_mov_b32_e32 v112, v0
	v_mov_b32_e32 v113, v0
	v_mov_b32_e32 v114, v0
	v_mov_b32_e32 v115, v0
	v_mov_b32_e32 v116, v0
	v_mov_b32_e32 v117, v0
	v_mov_b32_e32 v118, v0
	v_mov_b32_e32 v119, v0
	v_mov_b32_e32 v120, v0
	v_mov_b32_e32 v121, v0
	v_mov_b32_e32 v122, v0
	v_mov_b32_e32 v123, v0
	v_mov_b32_e32 v124, v0
	v_mov_b32_e32 v125, v0
	v_mov_b32_e32 v126, v0
	v_mov_b32_e32 v127, v0
	s_and_b64 vcc, exec, s[94:95]
	s_cbranch_vccnz .Lprio_a
	s_setprio 1
.Lprio_a:
.LBB0_380:
	s_add_i32 s97, s38, 2
	s_add_u32 s98, s6, 0x80
	s_addc_u32 s39, s7, 0
	s_cmp_eq_u32 s41, s38
	s_cselect_b32 s39, s47, s39
	s_cselect_b32 s38, s46, s98
	s_cselect_b32 s99, s61, s62
	s_cselect_b32 s98, s60, s49
	s_add_i32 vcc_lo, 0, 0x14000
	v_add_u32_e32 v164, s42, v180
	v_add_u32_e32 v176, vcc_lo, v180
	ds_read_b128 v[128:131], v164
	ds_read_b128 v[132:135], v164 offset:1024
	ds_read_b128 v[136:139], v164 offset:2048
	ds_read_b128 v[164:167], v164 offset:3072
	ds_read_b128 v[168:171], v176
	ds_read_b128 v[172:175], v176 offset:1024
	ds_read_b128 v[182:185], v176 offset:2048
	ds_read_b128 v[186:189], v176 offset:3072
	v_lshl_add_u64 v[178:179], s[6:7], 0, v[162:163]
	s_add_i32 m0, s36, 0xc000
	ds_read_b128 v[190:193], v181
	ds_read_b128 v[194:197], v181 offset:1024
	ds_read_b128 v[198:201], v181 offset:2048
	ds_read_b128 v[202:205], v181 offset:3072
	ds_read_b128 v[206:209], v181 offset:4096
	ds_read_b128 v[212:215], v181 offset:5120
	ds_read_b128 v[216:219], v181 offset:6144
	ds_read_b128 v[220:223], v181 offset:7168
	global_load_lds_dwordx4 v[178:179], off
	v_lshl_add_u64 v[178:179], s[6:7], 0, v[160:161]
	s_add_i32 m0, s36, 0xe000
	s_nop 0
	global_load_lds_dwordx4 v[178:179], off
	s_waitcnt vmcnt(8)
	s_waitcnt lgkmcnt(0)
	s_barrier
	s_waitcnt lgkmcnt(0)
	v_mfma_f32_16x16x32_bf16 v[124:127], v[128:131], v[190:193], v[124:127]
	v_mfma_f32_16x16x32_bf16 v[120:123], v[136:139], v[190:193], v[120:123]
	v_mfma_f32_16x16x32_bf16 v[116:119], v[128:131], v[198:201], v[116:119]
	v_mfma_f32_16x16x32_bf16 v[112:115], v[136:139], v[198:201], v[112:115]
	v_mfma_f32_16x16x32_bf16 v[100:103], v[128:131], v[206:209], v[100:103]
	v_mfma_f32_16x16x32_bf16 v[96:99], v[136:139], v[206:209], v[96:99]
	v_mfma_f32_16x16x32_bf16 v[84:87], v[128:131], v[216:219], v[84:87]
	v_mfma_f32_16x16x32_bf16 v[80:83], v[136:139], v[216:219], v[80:83]
	v_mfma_f32_16x16x32_bf16 v[124:127], v[132:135], v[194:197], v[124:127]
	v_mfma_f32_16x16x32_bf16 v[120:123], v[164:167], v[194:197], v[120:123]
	v_mfma_f32_16x16x32_bf16 v[116:119], v[132:135], v[202:205], v[116:119]
	v_mfma_f32_16x16x32_bf16 v[112:115], v[164:167], v[202:205], v[112:115]
	v_mfma_f32_16x16x32_bf16 v[100:103], v[132:135], v[212:215], v[100:103]
	v_mfma_f32_16x16x32_bf16 v[96:99], v[164:167], v[212:215], v[96:99]
	v_mfma_f32_16x16x32_bf16 v[84:87], v[132:135], v[220:223], v[84:87]
	v_mfma_f32_16x16x32_bf16 v[80:83], v[164:167], v[220:223], v[80:83]
	v_mfma_f32_16x16x32_bf16 v[108:111], v[168:171], v[190:193], v[108:111]
	v_mfma_f32_16x16x32_bf16 v[104:107], v[182:185], v[190:193], v[104:107]
	v_mfma_f32_16x16x32_bf16 v[92:95], v[168:171], v[198:201], v[92:95]
	v_mfma_f32_16x16x32_bf16 v[88:91], v[182:185], v[198:201], v[88:91]
	v_mfma_f32_16x16x32_bf16 v[76:79], v[168:171], v[206:209], v[76:79]
	v_mfma_f32_16x16x32_bf16 v[72:75], v[182:185], v[206:209], v[72:75]
	v_mfma_f32_16x16x32_bf16 v[68:71], v[168:171], v[216:219], v[68:71]
	v_mfma_f32_16x16x32_bf16 v[64:67], v[182:185], v[216:219], v[64:67]
	v_mfma_f32_16x16x32_bf16 v[108:111], v[172:175], v[194:197], v[108:111]
	v_mfma_f32_16x16x32_bf16 v[104:107], v[186:189], v[194:197], v[104:107]
	v_mfma_f32_16x16x32_bf16 v[92:95], v[172:175], v[202:205], v[92:95]
	v_mfma_f32_16x16x32_bf16 v[88:91], v[186:189], v[202:205], v[88:91]
	v_mfma_f32_16x16x32_bf16 v[76:79], v[172:175], v[212:215], v[76:79]
	v_mfma_f32_16x16x32_bf16 v[72:75], v[186:189], v[212:215], v[72:75]
	v_mfma_f32_16x16x32_bf16 v[68:71], v[172:175], v[220:223], v[68:71]
	v_mfma_f32_16x16x32_bf16 v[64:67], v[186:189], v[220:223], v[64:67]
	s_barrier
; #define PG8_STAGE(bufoff, gbase, voff) do { _Pragma("unroll") for (int _i = 0; _i < 2; ++_i) \
;         __builtin_amdgcn_global_load_lds((const unsigned*)((const char*)(gbase) + (voff)[_i]), (PG8_LAS unsigned*)(lds + (bufoff) + ldsw + _i * 8192), 16, 0, 0); } while (0)
; #define PG8_LDA(dst, b, h) do { _Pragma("unroll") for (int m = 0; m < 4; ++m) _Pragma("unroll") for (int k = 0; k < 2; ++k) dst[m][k] = *(const PG8_LAS bf16x8*)(lds + PG8_SA(b, h) + aoff + m * 2048 + k * 1024); } while (0)
; #define PG8_LDB(dst, b, h) do { _Pragma("unroll") for (int n = 0; n < 2; ++n) _Pragma("unroll") for (int k = 0; k < 2; ++k) dst[n][k] = *(const PG8_LAS bf16x8*)(lds + PG8_SB(b, h) + boff + n * 2048 + k * 1024); } while (0)
; #define PG8_MMA(ai, bj, At, Bt) do { __builtin_amdgcn_s_setprio(1); _Pragma("unroll") for (int m = 0; m < 4; ++m) _Pragma("unroll") for (int n = 0; n < 2; ++n) _Pragma("unroll") for (int k = 0; k < 2; ++k) \
;         acc[ai][bj][m][n] = __builtin_amdgcn_mfma_f32_16x16x32_bf16(Bt[n][k], At[m][k], acc[ai][bj][m][n], 0, 0, 0); __builtin_amdgcn_s_setprio(0); } while (0)
; #define PG8_WAIT_V(n) asm volatile("s_waitcnt vmcnt(" #n ")" ::: "memory")
; #define PG8_WAIT_L(n) asm volatile("s_waitcnt lgkmcnt(" #n ")" ::: "memory")
; #define PG8_BAR __builtin_amdgcn_s_barrier()
; #define PG8_SCHED __builtin_amdgcn_sched_barrier(0)
; template <class Epi, class Sched, bool ALIGN_EPI = false, bool SP2 = false>
; __device__ __forceinline__ void gemm_phase(PG8_LAS unsigned char* lds, const Gemm g, const Sched& S, const Epi& E, const int wid_) {
;     ...
;             PG8_LDA(At, 0, 1); PG8_STAGE(PG8_SB(0, 0), b2, voffB); PG8_STAGE(PG8_SB(0, 1), b2 + hstepB, voffB); PG8_STAGE(PG8_SA(0, 0), a2, voffA);
;             PG8_WAIT_V(8); PG8_WAIT_L(0); PG8_BAR; PG8_MMA(1, 0, At, B0); PG8_MMA(1, 1, At, B1); PG8_BAR; PG8_SCHED;
;             PG8_LDB(B0, 1, 0); PG8_LDB(B1, 1, 1); PG8_SCHED; PG8_LDA(At, 1, 0); PG8_STAGE(PG8_SA(0, 1), a2 + hstepA, voffA);
	s_add_i32 vcc_hi, s42, s83
	v_lshl_add_u64 v[178:179], s[98:99], 0, v[142:143]
	s_mov_b32 m0, vcc_hi
	ds_read_b128 v[190:193], v181 offset:16384
	ds_read_b128 v[194:197], v181 offset:17408
	ds_read_b128 v[198:201], v181 offset:18432
	ds_read_b128 v[202:205], v181 offset:19456
	ds_read_b128 v[206:209], v181 offset:20480
	ds_read_b128 v[212:215], v181 offset:21504
	ds_read_b128 v[216:219], v181 offset:22528
	ds_read_b128 v[220:223], v181 offset:23552
	global_load_lds_dwordx4 v[178:179], off
	s_add_i32 m0, vcc_hi, 0x2000
	v_lshl_add_u64 v[224:225], s[98:99], 0, v[146:147]
	s_add_u32 s98, s98, s18
	s_addc_u32 s99, s99, 0
	s_add_i32 vcc_lo, vcc_lo, s83
	global_load_lds_dwordx4 v[224:225], off
	v_lshl_add_u64 v[226:227], s[98:99], 0, v[142:143]
	s_mov_b32 m0, vcc_lo
	v_lshl_add_u64 v[228:229], s[98:99], 0, v[146:147]
	global_load_lds_dwordx4 v[226:227], off
	s_add_i32 m0, vcc_lo, 0x2000
	v_lshl_add_u64 v[230:231], s[38:39], 0, v[140:141]
	global_load_lds_dwordx4 v[228:229], off
	s_mov_b32 m0, s36
	v_lshl_add_u64 v[232:233], s[38:39], 0, v[144:145]
	global_load_lds_dwordx4 v[230:231], off
	s_mov_b32 m0, s10
	s_nop 0
	global_load_lds_dwordx4 v[232:233], off
	s_waitcnt vmcnt(8)
	s_waitcnt lgkmcnt(0)
	s_barrier
	s_waitcnt lgkmcnt(0)
	v_mfma_f32_16x16x32_bf16 v[60:63], v[128:131], v[190:193], v[60:63]
	v_mfma_f32_16x16x32_bf16 v[56:59], v[136:139], v[190:193], v[56:59]
	v_mfma_f32_16x16x32_bf16 v[52:55], v[128:131], v[198:201], v[52:55]
	v_mfma_f32_16x16x32_bf16 v[48:51], v[136:139], v[198:201], v[48:51]
	v_mfma_f32_16x16x32_bf16 v[36:39], v[128:131], v[206:209], v[36:39]
	v_mfma_f32_16x16x32_bf16 v[32:35], v[136:139], v[206:209], v[32:35]
	v_mfma_f32_16x16x32_bf16 v[20:23], v[128:131], v[216:219], v[20:23]
	v_mfma_f32_16x16x32_bf16 v[16:19], v[136:139], v[216:219], v[16:19]
	v_mfma_f32_16x16x32_bf16 v[60:63], v[132:135], v[194:197], v[60:63]
	v_mfma_f32_16x16x32_bf16 v[56:59], v[164:167], v[194:197], v[56:59]
	v_mfma_f32_16x16x32_bf16 v[52:55], v[132:135], v[202:205], v[52:55]
	v_mfma_f32_16x16x32_bf16 v[48:51], v[164:167], v[202:205], v[48:51]
	v_mfma_f32_16x16x32_bf16 v[36:39], v[132:135], v[212:215], v[36:39]
	v_mfma_f32_16x16x32_bf16 v[32:35], v[164:167], v[212:215], v[32:35]
	v_mfma_f32_16x16x32_bf16 v[20:23], v[132:135], v[220:223], v[20:23]
	v_mfma_f32_16x16x32_bf16 v[16:19], v[164:167], v[220:223], v[16:19]
	v_mfma_f32_16x16x32_bf16 v[44:47], v[168:171], v[190:193], v[44:47]
	v_mfma_f32_16x16x32_bf16 v[40:43], v[182:185], v[190:193], v[40:43]
	v_mfma_f32_16x16x32_bf16 v[28:31], v[168:171], v[198:201], v[28:31]
	v_mfma_f32_16x16x32_bf16 v[24:27], v[182:185], v[198:201], v[24:27]
	v_mfma_f32_16x16x32_bf16 v[12:15], v[168:171], v[206:209], v[12:15]
	v_mfma_f32_16x16x32_bf16 v[8:11], v[182:185], v[206:209], v[8:11]
	v_mfma_f32_16x16x32_bf16 v[4:7], v[168:171], v[216:219], v[4:7]
	v_mfma_f32_16x16x32_bf16 v[0:3], v[182:185], v[216:219], v[0:3]
	v_mfma_f32_16x16x32_bf16 v[44:47], v[172:175], v[194:197], v[44:47]
	v_mfma_f32_16x16x32_bf16 v[40:43], v[186:189], v[194:197], v[40:43]
	v_mfma_f32_16x16x32_bf16 v[28:31], v[172:175], v[202:205], v[28:31]
	v_mfma_f32_16x16x32_bf16 v[24:27], v[186:189], v[202:205], v[24:27]
	v_mfma_f32_16x16x32_bf16 v[12:15], v[172:175], v[212:215], v[12:15]
	v_mfma_f32_16x16x32_bf16 v[8:11], v[186:189], v[212:215], v[8:11]
	v_mfma_f32_16x16x32_bf16 v[4:7], v[172:175], v[220:223], v[4:7]
	v_mfma_f32_16x16x32_bf16 v[0:3], v[186:189], v[220:223], v[0:3]
	s_barrier
	s_add_i32 s98, 0, 0x18000
	s_add_i32 s99, 0, 0x1c000
	v_add_u32_e32 v164, s98, v180
	v_add_u32_e32 v176, s99, v180
	ds_read_b128 v[128:131], v164
	ds_read_b128 v[132:135], v164 offset:1024
	ds_read_b128 v[136:139], v164 offset:2048
	ds_read_b128 v[164:167], v164 offset:3072
	ds_read_b128 v[168:171], v176
	ds_read_b128 v[172:175], v176 offset:1024
	ds_read_b128 v[182:185], v176 offset:2048
	ds_read_b128 v[186:189], v176 offset:3072
	s_add_u32 s38, s38, s88
	s_addc_u32 s39, s39, 0
	s_mov_b32 m0, s11
	v_lshl_add_u64 v[234:235], s[38:39], 0, v[140:141]
	ds_read_b128 v[190:193], v181 offset:32768
	ds_read_b128 v[194:197], v181 offset:33792
	ds_read_b128 v[198:201], v181 offset:34816
	ds_read_b128 v[202:205], v181 offset:35840
	ds_read_b128 v[206:209], v181 offset:36864
	ds_read_b128 v[212:215], v181 offset:37888
	ds_read_b128 v[216:219], v181 offset:38912
	ds_read_b128 v[220:223], v181 offset:39936
	global_load_lds_dwordx4 v[234:235], off
	v_lshl_add_u64 v[234:235], s[38:39], 0, v[144:145]
	s_mov_b32 m0, s55
	s_nop 0
	global_load_lds_dwordx4 v[234:235], off
	s_waitcnt vmcnt(8)
	s_waitcnt lgkmcnt(0)
	s_barrier
; #define PG8_STAGE(bufoff, gbase, voff) do { _Pragma("unroll") for (int _i = 0; _i < 2; ++_i) \
;         __builtin_amdgcn_global_load_lds((const unsigned*)((const char*)(gbase) + (voff)[_i]), (PG8_LAS unsigned*)(lds + (bufoff) + ldsw + _i * 8192), 16, 0, 0); } while (0)
; #define PG8_LDA(dst, b, h) do { _Pragma("unroll") for (int m = 0; m < 4; ++m) _Pragma("unroll") for (int k = 0; k < 2; ++k) dst[m][k] = *(const PG8_LAS bf16x8*)(lds + PG8_SA(b, h) + aoff + m * 2048 + k * 1024); } while (0)
; #define PG8_MMA(ai, bj, At, Bt) do { __builtin_amdgcn_s_setprio(1); _Pragma("unroll") for (int m = 0; m < 4; ++m) _Pragma("unroll") for (int n = 0; n < 2; ++n) _Pragma("unroll") for (int k = 0; k < 2; ++k) \
;         acc[ai][bj][m][n] = __builtin_amdgcn_mfma_f32_16x16x32_bf16(Bt[n][k], At[m][k], acc[ai][bj][m][n], 0, 0, 0); __builtin_amdgcn_s_setprio(0); } while (0)
; #define PG8_WAIT_V(n) asm volatile("s_waitcnt vmcnt(" #n ")" ::: "memory")
; #define PG8_WAIT_L(n) asm volatile("s_waitcnt lgkmcnt(" #n ")" ::: "memory")
; #define PG8_BAR __builtin_amdgcn_s_barrier()
; #define PG8_SCHED __builtin_amdgcn_sched_barrier(0)
; template <class Epi, class Sched, bool ALIGN_EPI = false, bool SP2 = false>
; __device__ __forceinline__ void gemm_phase(PG8_LAS unsigned char* lds, const Gemm g, const Sched& S, const Epi& E, const int wid_) {
;     ...
;             PG8_WAIT_V(8); PG8_WAIT_L(0); PG8_BAR; PG8_MMA(0, 0, At, B0); PG8_MMA(0, 1, At, B1); PG8_BAR; PG8_SCHED;
;             PG8_LDA(At, 1, 1); PG8_STAGE(PG8_SB(1, 0), b3, voffB); PG8_STAGE(PG8_SB(1, 1), b3 + hstepB, voffB); PG8_STAGE(PG8_SA(1, 0), a3, voffA);
;             PG8_WAIT_V(8); PG8_WAIT_L(0); PG8_BAR; PG8_MMA(1, 0, At, B0); PG8_MMA(1, 1, At, B1); PG8_BAR; PG8_SCHED;
	s_waitcnt lgkmcnt(0)
	v_mfma_f32_16x16x32_bf16 v[124:127], v[128:131], v[190:193], v[124:127]
	v_mfma_f32_16x16x32_bf16 v[120:123], v[136:139], v[190:193], v[120:123]
	v_mfma_f32_16x16x32_bf16 v[116:119], v[128:131], v[198:201], v[116:119]
	v_mfma_f32_16x16x32_bf16 v[112:115], v[136:139], v[198:201], v[112:115]
	v_mfma_f32_16x16x32_bf16 v[100:103], v[128:131], v[206:209], v[100:103]
	v_mfma_f32_16x16x32_bf16 v[96:99], v[136:139], v[206:209], v[96:99]
	v_mfma_f32_16x16x32_bf16 v[84:87], v[128:131], v[216:219], v[84:87]
	v_mfma_f32_16x16x32_bf16 v[80:83], v[136:139], v[216:219], v[80:83]
	v_mfma_f32_16x16x32_bf16 v[124:127], v[132:135], v[194:197], v[124:127]
	v_mfma_f32_16x16x32_bf16 v[120:123], v[164:167], v[194:197], v[120:123]
	v_mfma_f32_16x16x32_bf16 v[116:119], v[132:135], v[202:205], v[116:119]
	v_mfma_f32_16x16x32_bf16 v[112:115], v[164:167], v[202:205], v[112:115]
	v_mfma_f32_16x16x32_bf16 v[100:103], v[132:135], v[212:215], v[100:103]
	v_mfma_f32_16x16x32_bf16 v[96:99], v[164:167], v[212:215], v[96:99]
	v_mfma_f32_16x16x32_bf16 v[84:87], v[132:135], v[220:223], v[84:87]
	v_mfma_f32_16x16x32_bf16 v[80:83], v[164:167], v[220:223], v[80:83]
	v_mfma_f32_16x16x32_bf16 v[108:111], v[168:171], v[190:193], v[108:111]
	v_mfma_f32_16x16x32_bf16 v[104:107], v[182:185], v[190:193], v[104:107]
	v_mfma_f32_16x16x32_bf16 v[92:95], v[168:171], v[198:201], v[92:95]
	v_mfma_f32_16x16x32_bf16 v[88:91], v[182:185], v[198:201], v[88:91]
	v_mfma_f32_16x16x32_bf16 v[76:79], v[168:171], v[206:209], v[76:79]
	v_mfma_f32_16x16x32_bf16 v[72:75], v[182:185], v[206:209], v[72:75]
	v_mfma_f32_16x16x32_bf16 v[68:71], v[168:171], v[216:219], v[68:71]
	v_mfma_f32_16x16x32_bf16 v[64:67], v[182:185], v[216:219], v[64:67]
	v_mfma_f32_16x16x32_bf16 v[108:111], v[172:175], v[194:197], v[108:111]
	v_mfma_f32_16x16x32_bf16 v[104:107], v[186:189], v[194:197], v[104:107]
	v_mfma_f32_16x16x32_bf16 v[92:95], v[172:175], v[202:205], v[92:95]
	v_mfma_f32_16x16x32_bf16 v[88:91], v[186:189], v[202:205], v[88:91]
	v_mfma_f32_16x16x32_bf16 v[76:79], v[172:175], v[212:215], v[76:79]
	v_mfma_f32_16x16x32_bf16 v[72:75], v[186:189], v[212:215], v[72:75]
	v_mfma_f32_16x16x32_bf16 v[68:71], v[172:175], v[220:223], v[68:71]
	v_mfma_f32_16x16x32_bf16 v[64:67], v[186:189], v[220:223], v[64:67]
	s_barrier
	s_add_i32 s38, s98, s83
	v_lshl_add_u64 v[178:179], v[178:179], 0, s[66:67]
	s_mov_b32 m0, s38
	ds_read_b128 v[190:193], v181 offset:49152
	ds_read_b128 v[194:197], v181 offset:50176
	ds_read_b128 v[198:201], v181 offset:51200
	ds_read_b128 v[202:205], v181 offset:52224
	ds_read_b128 v[206:209], v181 offset:53248
	ds_read_b128 v[212:215], v181 offset:54272
	ds_read_b128 v[216:219], v181 offset:55296
	ds_read_b128 v[220:223], v181 offset:56320
	global_load_lds_dwordx4 v[178:179], off
	v_lshl_add_u64 v[178:179], v[224:225], 0, s[66:67]
	s_add_i32 m0, s38, 0x2000
	s_add_i32 s38, s99, s83
	global_load_lds_dwordx4 v[178:179], off
	v_lshl_add_u64 v[178:179], v[226:227], 0, s[66:67]
	s_mov_b32 m0, s38
	s_nop 0
	global_load_lds_dwordx4 v[178:179], off
	v_lshl_add_u64 v[178:179], v[228:229], 0, s[66:67]
	s_add_i32 m0, s38, 0x2000
	s_nop 0
	global_load_lds_dwordx4 v[178:179], off
	v_lshl_add_u64 v[178:179], v[230:231], 0, s[66:67]
	s_mov_b32 m0, s33
	s_nop 0
	global_load_lds_dwordx4 v[178:179], off
	v_lshl_add_u64 v[178:179], v[232:233], 0, s[66:67]
	s_mov_b32 m0, s52
	s_nop 0
	global_load_lds_dwordx4 v[178:179], off
	s_waitcnt vmcnt(8)
	s_waitcnt lgkmcnt(0)
	s_barrier
	s_waitcnt lgkmcnt(0)
	v_mfma_f32_16x16x32_bf16 v[60:63], v[128:131], v[190:193], v[60:63]
	v_mfma_f32_16x16x32_bf16 v[56:59], v[136:139], v[190:193], v[56:59]
	v_mfma_f32_16x16x32_bf16 v[52:55], v[128:131], v[198:201], v[52:55]
	v_mfma_f32_16x16x32_bf16 v[48:51], v[136:139], v[198:201], v[48:51]
	v_mfma_f32_16x16x32_bf16 v[36:39], v[128:131], v[206:209], v[36:39]
	v_mfma_f32_16x16x32_bf16 v[32:35], v[136:139], v[206:209], v[32:35]
	v_mfma_f32_16x16x32_bf16 v[20:23], v[128:131], v[216:219], v[20:23]
	v_mfma_f32_16x16x32_bf16 v[16:19], v[136:139], v[216:219], v[16:19]
	v_mfma_f32_16x16x32_bf16 v[60:63], v[132:135], v[194:197], v[60:63]
	v_mfma_f32_16x16x32_bf16 v[56:59], v[164:167], v[194:197], v[56:59]
	v_mfma_f32_16x16x32_bf16 v[52:55], v[132:135], v[202:205], v[52:55]
	v_mfma_f32_16x16x32_bf16 v[48:51], v[164:167], v[202:205], v[48:51]
	v_mfma_f32_16x16x32_bf16 v[36:39], v[132:135], v[212:215], v[36:39]
	v_mfma_f32_16x16x32_bf16 v[32:35], v[164:167], v[212:215], v[32:35]
	v_mfma_f32_16x16x32_bf16 v[20:23], v[132:135], v[220:223], v[20:23]
	v_mfma_f32_16x16x32_bf16 v[16:19], v[164:167], v[220:223], v[16:19]
	v_mfma_f32_16x16x32_bf16 v[44:47], v[168:171], v[190:193], v[44:47]
	v_mfma_f32_16x16x32_bf16 v[40:43], v[182:185], v[190:193], v[40:43]
	v_mfma_f32_16x16x32_bf16 v[28:31], v[168:171], v[198:201], v[28:31]
	v_mfma_f32_16x16x32_bf16 v[24:27], v[182:185], v[198:201], v[24:27]
	v_mfma_f32_16x16x32_bf16 v[12:15], v[168:171], v[206:209], v[12:15]
	v_mfma_f32_16x16x32_bf16 v[8:11], v[182:185], v[206:209], v[8:11]
	v_mfma_f32_16x16x32_bf16 v[4:7], v[168:171], v[216:219], v[4:7]
	v_mfma_f32_16x16x32_bf16 v[0:3], v[182:185], v[216:219], v[0:3]
	v_mfma_f32_16x16x32_bf16 v[44:47], v[172:175], v[194:197], v[44:47]
	v_mfma_f32_16x16x32_bf16 v[40:43], v[186:189], v[194:197], v[40:43]
	v_mfma_f32_16x16x32_bf16 v[28:31], v[172:175], v[202:205], v[28:31]
	v_mfma_f32_16x16x32_bf16 v[24:27], v[186:189], v[202:205], v[24:27]
	v_mfma_f32_16x16x32_bf16 v[12:15], v[172:175], v[212:215], v[12:15]
	v_mfma_f32_16x16x32_bf16 v[8:11], v[186:189], v[212:215], v[8:11]
	v_mfma_f32_16x16x32_bf16 v[4:7], v[172:175], v[220:223], v[4:7]
	v_mfma_f32_16x16x32_bf16 v[0:3], v[186:189], v[220:223], v[0:3]
	s_barrier
	s_add_u32 s49, s49, 0x100
	s_addc_u32 s62, s62, 0
	s_add_u32 s6, s6, 0x100
	s_addc_u32 s7, s7, 0
	s_cmp_ge_u32 s97, s71
	s_mov_b32 s38, s97
	s_cbranch_scc0 .LBB0_380
	s_setprio 0
	s_and_b64 vcc, exec, s[94:95]
	s_cbranch_vccz .LBB0_384
	s_barrier
	v_lshl_add_u32 v164, s48, 8, v153
	s_cmp_lt_i32 s37, 2
	s_mov_b64 s[6:7], -1
	s_cbranch_scc0 .LBB0_385

; template <class Epi, class Sched, bool ALIGN_EPI = false, bool SP2 = false>
; __device__ __forceinline__ void gemm_phase(PG8_LAS unsigned char* lds, const Gemm g, const Sched& S, const Epi& E, const int wid_) {
;     ...
; #pragma unroll
;     for (int a = 0; a < 2; ++a)
; #pragma unroll
;         for (int b = 0; b < 2; ++b)
; #pragma unroll
;             for (int m = 0; m < 4; ++m)
; #pragma unroll
;                 for (int n = 0; n < 2; ++n) acc[a][b][m][n] = (f32x4){0.f, 0.f, 0.f, 0.f};
;     bf16x8 At[4][2], B0[2][2], B1[2][2];
;     const char* cA = (const char*)g.A + (size_t)cur.pm * tstepA; const char* cB = (const char*)g.Bt + (size_t)cur.pn * tstepB;
;     S.a_ready(cur);
;     if constexpr (SP2) {
;         PG8_STAGE(PG8_SB(0, 0), cB, voffB); PG8_STAGE(PG8_SB(0, 1), cB + hstepB, voffB); PG8_STAGE(PG8_SA(0, 0), cA, voffA); PG8_STAGE(PG8_SA(0, 1), cA + hstepA, voffA);
;         if (wr == 1) PG8_BAR;
;         PG8_WAIT_V(2); PG8_BAR;
;         PG8_STAGE(PG8_SB(1, 0), cB + kstep, voffB); PG8_STAGE(PG8_SA(1, 0), cA + kstep, voffA); PG8_STAGE(PG8_SB(1, 1), cB + hstepB + kstep, voffB);
;         PG8_WAIT_V(6); PG8_BAR;
;     } else {
;         PG8_STAGE(PG8_SB(0, 0), cB, voffB); PG8_STAGE(PG8_SA(0, 0), cA, voffA); PG8_STAGE(PG8_SB(0, 1), cB + hstepB, voffB); PG8_STAGE(PG8_SA(0, 1), cA + hstepA, voffA);
;         if (wr == 1) PG8_BAR;
;         PG8_WAIT_V(4); PG8_BAR;
;         PG8_STAGE(PG8_SB(1, 0), cB + kstep, voffB); PG8_STAGE(PG8_SA(1, 0), cA + kstep, voffA); PG8_STAGE(PG8_SB(1, 1), cB + hstepB + kstep, voffB);
;         PG8_WAIT_V(6); PG8_BAR;
;     }
;     for (;;) {
;         const bool has_next = S.next(ui + 1, nxt);
;         const char* nA = has_next ? (const char*)g.A + (size_t)nxt.pm * tstepA : cA; const char* nB = has_next ? (const char*)g.Bt + (size_t)nxt.pn * tstepB : cB;
;         for (int t = 0; t < nt; t += 2) {
;             const bool last = (t == nt - 2);
;             const char* a1 = cA + (size_t)(t + 1) * kstep;
;             const char* a2 = last ? nA : cA + (size_t)(t + 2) * kstep; const char* b2 = last ? nB : cB + (size_t)(t + 2) * kstep;
;             const char* a3 = a2 + kstep; const char* b3 = b2 + kstep;
;             if (last && has_next) S.a_ready(nxt);
;             if constexpr (SP2) {
;             PG8_LDB(B0, 0, 0); PG8_LDB(B1, 0, 1); PG8_SCHED; PG8_LDA(At, 0, 0); PG8_STAGE(PG8_SA(1, 1), a1 + hstepA, voffA);
.LBB0_613:
	s_add_u32 s11, s8, 0x100
	s_addc_u32 s76, s9, 0
	s_add_u32 s6, s38, 0x80
	v_mov_b32_e32 v0, 0
	s_addc_u32 s7, s39, 0
	s_mov_b32 s8, 0
	v_mov_b32_e32 v1, v0
	v_mov_b32_e32 v2, v0
	v_mov_b32_e32 v3, v0
	v_mov_b32_e32 v4, v0
	v_mov_b32_e32 v5, v0
	v_mov_b32_e32 v6, v0
	v_mov_b32_e32 v7, v0
	v_mov_b32_e32 v16, v0
	v_mov_b32_e32 v17, v0
	v_mov_b32_e32 v18, v0
	v_mov_b32_e32 v19, v0
	v_mov_b32_e32 v20, v0
	v_mov_b32_e32 v21, v0
	v_mov_b32_e32 v22, v0
	v_mov_b32_e32 v23, v0
	v_mov_b32_e32 v32, v0
	v_mov_b32_e32 v33, v0
	v_mov_b32_e32 v34, v0
	v_mov_b32_e32 v35, v0
	v_mov_b32_e32 v36, v0
	v_mov_b32_e32 v37, v0
	v_mov_b32_e32 v38, v0
	v_mov_b32_e32 v39, v0
	v_mov_b32_e32 v48, v0
	v_mov_b32_e32 v49, v0
	v_mov_b32_e32 v50, v0
	v_mov_b32_e32 v51, v0
	v_mov_b32_e32 v52, v0
	v_mov_b32_e32 v53, v0
	v_mov_b32_e32 v54, v0
	v_mov_b32_e32 v55, v0
	v_mov_b32_e32 v8, v0
	v_mov_b32_e32 v9, v0
	v_mov_b32_e32 v10, v0
	v_mov_b32_e32 v11, v0
	v_mov_b32_e32 v12, v0
	v_mov_b32_e32 v13, v0
	v_mov_b32_e32 v14, v0
	v_mov_b32_e32 v15, v0
	v_mov_b32_e32 v24, v0
	v_mov_b32_e32 v25, v0
	v_mov_b32_e32 v26, v0
	v_mov_b32_e32 v27, v0
	v_mov_b32_e32 v28, v0
	v_mov_b32_e32 v29, v0
	v_mov_b32_e32 v30, v0
	v_mov_b32_e32 v31, v0
	v_mov_b32_e32 v40, v0
	v_mov_b32_e32 v41, v0
	v_mov_b32_e32 v42, v0
	v_mov_b32_e32 v43, v0
	v_mov_b32_e32 v44, v0
	v_mov_b32_e32 v45, v0
	v_mov_b32_e32 v46, v0
	v_mov_b32_e32 v47, v0
	v_mov_b32_e32 v56, v0
	v_mov_b32_e32 v57, v0
	v_mov_b32_e32 v58, v0
	v_mov_b32_e32 v59, v0
	v_mov_b32_e32 v60, v0
	v_mov_b32_e32 v61, v0
	v_mov_b32_e32 v62, v0
	v_mov_b32_e32 v63, v0
	v_mov_b32_e32 v64, v0
	v_mov_b32_e32 v65, v0
	v_mov_b32_e32 v66, v0
	v_mov_b32_e32 v67, v0
	v_mov_b32_e32 v68, v0
	v_mov_b32_e32 v69, v0
	v_mov_b32_e32 v70, v0
	v_mov_b32_e32 v71, v0
	v_mov_b32_e32 v80, v0
	v_mov_b32_e32 v81, v0
	v_mov_b32_e32 v82, v0
	v_mov_b32_e32 v83, v0
	v_mov_b32_e32 v84, v0
	v_mov_b32_e32 v85, v0
	v_mov_b32_e32 v86, v0
	v_mov_b32_e32 v87, v0
	v_mov_b32_e32 v96, v0
	v_mov_b32_e32 v97, v0
	v_mov_b32_e32 v98, v0
	v_mov_b32_e32 v99, v0
	v_mov_b32_e32 v100, v0
	v_mov_b32_e32 v101, v0
	v_mov_b32_e32 v102, v0
	v_mov_b32_e32 v103, v0
	v_mov_b32_e32 v120, v0
	v_mov_b32_e32 v121, v0
	v_mov_b32_e32 v122, v0
	v_mov_b32_e32 v123, v0
	v_mov_b32_e32 v128, v0
	v_mov_b32_e32 v129, v0
	v_mov_b32_e32 v130, v0
	v_mov_b32_e32 v131, v0
	v_mov_b32_e32 v72, v0
	v_mov_b32_e32 v73, v0
	v_mov_b32_e32 v74, v0
	v_mov_b32_e32 v75, v0
	v_mov_b32_e32 v76, v0
	v_mov_b32_e32 v77, v0
	v_mov_b32_e32 v78, v0
	v_mov_b32_e32 v79, v0
	v_mov_b32_e32 v88, v0
	v_mov_b32_e32 v89, v0
	v_mov_b32_e32 v90, v0
	v_mov_b32_e32 v91, v0
	v_mov_b32_e32 v92, v0
	v_mov_b32_e32 v93, v0
	v_mov_b32_e32 v94, v0
	v_mov_b32_e32 v95, v0
	v_mov_b32_e32 v108, v0
	v_mov_b32_e32 v109, v0
	v_mov_b32_e32 v110, v0
	v_mov_b32_e32 v111, v0
	v_mov_b32_e32 v116, v0
	v_mov_b32_e32 v117, v0
	v_mov_b32_e32 v118, v0
	v_mov_b32_e32 v119, v0
	v_mov_b32_e32 v136, v0
	v_mov_b32_e32 v137, v0
	v_mov_b32_e32 v138, v0
	v_mov_b32_e32 v139, v0
	v_mov_b32_e32 v140, v0
	v_mov_b32_e32 v141, v0
	v_mov_b32_e32 v142, v0
	v_mov_b32_e32 v143, v0
	s_and_b64 vcc, exec, s[36:37]
	s_cbranch_vccnz .Lprio_b
	s_setprio 1
.Lprio_b:
.LBB0_614:
	s_add_i32 s38, s8, 2
	s_add_u32 s39, s6, 0x80
	s_addc_u32 s9, s7, 0
	s_cmp_eq_u32 s80, s8
	s_cselect_b32 s9, s73, s9
	s_cselect_b32 s8, s72, s39
	s_cselect_b32 s87, s75, s76
	s_cselect_b32 s86, s74, s11
	s_add_i32 s39, 0, 0x14000
	v_add_u32_e32 v132, s42, v246
	v_add_u32_e32 v156, s39, v246
	ds_read_b128 v[104:107], v132
	ds_read_b128 v[112:115], v132 offset:1024
	ds_read_b128 v[124:127], v132 offset:2048
	ds_read_b128 v[132:135], v132 offset:3072
	ds_read_b128 v[144:147], v156
	ds_read_b128 v[148:151], v156 offset:1024
	ds_read_b128 v[152:155], v156 offset:2048
	ds_read_b128 v[156:159], v156 offset:3072
	v_lshl_add_u64 v[194:195], s[6:7], 0, v[216:217]
	s_add_i32 m0, s41, 0xc000
	ds_read_b128 v[160:163], v247
	ds_read_b128 v[164:167], v247 offset:1024
	ds_read_b128 v[168:171], v247 offset:2048
	ds_read_b128 v[172:175], v247 offset:3072
	ds_read_b128 v[178:181], v247 offset:4096
	ds_read_b128 v[182:185], v247 offset:5120
	ds_read_b128 v[186:189], v247 offset:6144
	ds_read_b128 v[190:193], v247 offset:7168
	global_load_lds_dwordx4 v[194:195], off
	v_lshl_add_u64 v[194:195], s[6:7], 0, v[214:215]
	s_add_i32 m0, s41, 0xe000
	s_nop 0
	global_load_lds_dwordx4 v[194:195], off
	s_waitcnt vmcnt(8)
	s_waitcnt lgkmcnt(0)
	s_barrier
	s_waitcnt lgkmcnt(0)
	v_mfma_f32_16x16x32_bf16 v[140:143], v[104:107], v[160:163], v[140:143]
	v_mfma_f32_16x16x32_bf16 v[136:139], v[124:127], v[160:163], v[136:139]
	v_mfma_f32_16x16x32_bf16 v[116:119], v[104:107], v[168:171], v[116:119]
	v_mfma_f32_16x16x32_bf16 v[108:111], v[124:127], v[168:171], v[108:111]
	v_mfma_f32_16x16x32_bf16 v[92:95], v[104:107], v[178:181], v[92:95]
	v_mfma_f32_16x16x32_bf16 v[88:91], v[124:127], v[178:181], v[88:91]
	v_mfma_f32_16x16x32_bf16 v[76:79], v[104:107], v[186:189], v[76:79]
	v_mfma_f32_16x16x32_bf16 v[72:75], v[124:127], v[186:189], v[72:75]
	v_mfma_f32_16x16x32_bf16 v[140:143], v[112:115], v[164:167], v[140:143]
	v_mfma_f32_16x16x32_bf16 v[136:139], v[132:135], v[164:167], v[136:139]
	v_mfma_f32_16x16x32_bf16 v[116:119], v[112:115], v[172:175], v[116:119]
	v_mfma_f32_16x16x32_bf16 v[108:111], v[132:135], v[172:175], v[108:111]
	v_mfma_f32_16x16x32_bf16 v[92:95], v[112:115], v[182:185], v[92:95]
	v_mfma_f32_16x16x32_bf16 v[88:91], v[132:135], v[182:185], v[88:91]
	v_mfma_f32_16x16x32_bf16 v[76:79], v[112:115], v[190:193], v[76:79]
	v_mfma_f32_16x16x32_bf16 v[72:75], v[132:135], v[190:193], v[72:75]
	v_mfma_f32_16x16x32_bf16 v[128:131], v[144:147], v[160:163], v[128:131]
	v_mfma_f32_16x16x32_bf16 v[120:123], v[152:155], v[160:163], v[120:123]
	v_mfma_f32_16x16x32_bf16 v[100:103], v[144:147], v[168:171], v[100:103]
	v_mfma_f32_16x16x32_bf16 v[96:99], v[152:155], v[168:171], v[96:99]
	v_mfma_f32_16x16x32_bf16 v[84:87], v[144:147], v[178:181], v[84:87]
	v_mfma_f32_16x16x32_bf16 v[80:83], v[152:155], v[178:181], v[80:83]
	v_mfma_f32_16x16x32_bf16 v[68:71], v[144:147], v[186:189], v[68:71]
	v_mfma_f32_16x16x32_bf16 v[64:67], v[152:155], v[186:189], v[64:67]
	v_mfma_f32_16x16x32_bf16 v[128:131], v[148:151], v[164:167], v[128:131]
	v_mfma_f32_16x16x32_bf16 v[120:123], v[156:159], v[164:167], v[120:123]
	v_mfma_f32_16x16x32_bf16 v[100:103], v[148:151], v[172:175], v[100:103]
	v_mfma_f32_16x16x32_bf16 v[96:99], v[156:159], v[172:175], v[96:99]
	v_mfma_f32_16x16x32_bf16 v[84:87], v[148:151], v[182:185], v[84:87]
	v_mfma_f32_16x16x32_bf16 v[80:83], v[156:159], v[182:185], v[80:83]
	v_mfma_f32_16x16x32_bf16 v[68:71], v[148:151], v[190:193], v[68:71]
	v_mfma_f32_16x16x32_bf16 v[64:67], v[156:159], v[190:193], v[64:67]
	s_barrier
; #define PG8_STAGE(bufoff, gbase, voff) do { _Pragma("unroll") for (int _i = 0; _i < 2; ++_i) \
;         __builtin_amdgcn_global_load_lds((const unsigned*)((const char*)(gbase) + (voff)[_i]), (PG8_LAS unsigned*)(lds + (bufoff) + ldsw + _i * 8192), 16, 0, 0); } while (0)
; #define PG8_LDA(dst, b, h) do { _Pragma("unroll") for (int m = 0; m < 4; ++m) _Pragma("unroll") for (int k = 0; k < 2; ++k) dst[m][k] = *(const PG8_LAS bf16x8*)(lds + PG8_SA(b, h) + aoff + m * 2048 + k * 1024); } while (0)
; #define PG8_LDB(dst, b, h) do { _Pragma("unroll") for (int n = 0; n < 2; ++n) _Pragma("unroll") for (int k = 0; k < 2; ++k) dst[n][k] = *(const PG8_LAS bf16x8*)(lds + PG8_SB(b, h) + boff + n * 2048 + k * 1024); } while (0)
; #define PG8_MMA(ai, bj, At, Bt) do { __builtin_amdgcn_s_setprio(1); _Pragma("unroll") for (int m = 0; m < 4; ++m) _Pragma("unroll") for (int n = 0; n < 2; ++n) _Pragma("unroll") for (int k = 0; k < 2; ++k) \
;         acc[ai][bj][m][n] = __builtin_amdgcn_mfma_f32_16x16x32_bf16(Bt[n][k], At[m][k], acc[ai][bj][m][n], 0, 0, 0); __builtin_amdgcn_s_setprio(0); } while (0)
; #define PG8_WAIT_V(n) asm volatile("s_waitcnt vmcnt(" #n ")" ::: "memory")
; #define PG8_WAIT_L(n) asm volatile("s_waitcnt lgkmcnt(" #n ")" ::: "memory")
; #define PG8_BAR __builtin_amdgcn_s_barrier()
; #define PG8_SCHED __builtin_amdgcn_sched_barrier(0)
; template <class Epi, class Sched, bool ALIGN_EPI = false, bool SP2 = false>
; __device__ __forceinline__ void gemm_phase(PG8_LAS unsigned char* lds, const Gemm g, const Sched& S, const Epi& E, const int wid_) {
;     ...
;             PG8_LDA(At, 0, 1); PG8_STAGE(PG8_SB(0, 0), b2, voffB); PG8_STAGE(PG8_SB(0, 1), b2 + hstepB, voffB); PG8_STAGE(PG8_SA(0, 0), a2, voffA);
;             PG8_WAIT_V(8); PG8_WAIT_L(0); PG8_BAR; PG8_MMA(1, 0, At, B0); PG8_MMA(1, 1, At, B1); PG8_BAR; PG8_SCHED;
;             PG8_LDB(B0, 1, 0); PG8_LDB(B1, 1, 1); PG8_SCHED; PG8_LDA(At, 1, 0); PG8_STAGE(PG8_SA(0, 1), a2 + hstepA, voffA);
	s_add_i32 s85, s42, s33
	v_lshl_add_u64 v[194:195], s[86:87], 0, v[176:177]
	s_mov_b32 m0, s85
	ds_read_b128 v[160:163], v247 offset:16384
	ds_read_b128 v[164:167], v247 offset:17408
	ds_read_b128 v[168:171], v247 offset:18432
	ds_read_b128 v[172:175], v247 offset:19456
	ds_read_b128 v[178:181], v247 offset:20480
	ds_read_b128 v[182:185], v247 offset:21504
	ds_read_b128 v[186:189], v247 offset:22528
	ds_read_b128 v[190:193], v247 offset:23552
	global_load_lds_dwordx4 v[194:195], off
	s_add_i32 m0, s85, 0x2000
	v_lshl_add_u64 v[196:197], s[86:87], 0, v[202:203]
	s_add_u32 s86, s86, s22
	s_addc_u32 s87, s87, 0
	s_add_i32 s39, s39, s33
	global_load_lds_dwordx4 v[196:197], off
	v_lshl_add_u64 v[198:199], s[86:87], 0, v[176:177]
	s_mov_b32 m0, s39
	v_lshl_add_u64 v[200:201], s[86:87], 0, v[202:203]
	global_load_lds_dwordx4 v[198:199], off
	s_add_i32 m0, s39, 0x2000
	v_lshl_add_u64 v[218:219], s[8:9], 0, v[206:207]
	global_load_lds_dwordx4 v[200:201], off
	s_mov_b32 m0, s41
	v_lshl_add_u64 v[220:221], s[8:9], 0, v[204:205]
	global_load_lds_dwordx4 v[218:219], off
	s_mov_b32 m0, s43
	s_nop 0
	global_load_lds_dwordx4 v[220:221], off
	s_waitcnt vmcnt(8)
	s_waitcnt lgkmcnt(0)
	s_barrier
	s_waitcnt lgkmcnt(0)
	v_mfma_f32_16x16x32_bf16 v[60:63], v[104:107], v[160:163], v[60:63]
	v_mfma_f32_16x16x32_bf16 v[56:59], v[124:127], v[160:163], v[56:59]
	v_mfma_f32_16x16x32_bf16 v[44:47], v[104:107], v[168:171], v[44:47]
	v_mfma_f32_16x16x32_bf16 v[40:43], v[124:127], v[168:171], v[40:43]
	v_mfma_f32_16x16x32_bf16 v[28:31], v[104:107], v[178:181], v[28:31]
	v_mfma_f32_16x16x32_bf16 v[24:27], v[124:127], v[178:181], v[24:27]
	v_mfma_f32_16x16x32_bf16 v[12:15], v[104:107], v[186:189], v[12:15]
	v_mfma_f32_16x16x32_bf16 v[8:11], v[124:127], v[186:189], v[8:11]
	v_mfma_f32_16x16x32_bf16 v[60:63], v[112:115], v[164:167], v[60:63]
	v_mfma_f32_16x16x32_bf16 v[56:59], v[132:135], v[164:167], v[56:59]
	v_mfma_f32_16x16x32_bf16 v[44:47], v[112:115], v[172:175], v[44:47]
	v_mfma_f32_16x16x32_bf16 v[40:43], v[132:135], v[172:175], v[40:43]
	v_mfma_f32_16x16x32_bf16 v[28:31], v[112:115], v[182:185], v[28:31]
	v_mfma_f32_16x16x32_bf16 v[24:27], v[132:135], v[182:185], v[24:27]
	v_mfma_f32_16x16x32_bf16 v[12:15], v[112:115], v[190:193], v[12:15]
	v_mfma_f32_16x16x32_bf16 v[8:11], v[132:135], v[190:193], v[8:11]
	v_mfma_f32_16x16x32_bf16 v[52:55], v[144:147], v[160:163], v[52:55]
	v_mfma_f32_16x16x32_bf16 v[48:51], v[152:155], v[160:163], v[48:51]
	v_mfma_f32_16x16x32_bf16 v[36:39], v[144:147], v[168:171], v[36:39]
	v_mfma_f32_16x16x32_bf16 v[32:35], v[152:155], v[168:171], v[32:35]
	v_mfma_f32_16x16x32_bf16 v[20:23], v[144:147], v[178:181], v[20:23]
	v_mfma_f32_16x16x32_bf16 v[16:19], v[152:155], v[178:181], v[16:19]
	v_mfma_f32_16x16x32_bf16 v[4:7], v[144:147], v[186:189], v[4:7]
	v_mfma_f32_16x16x32_bf16 v[0:3], v[152:155], v[186:189], v[0:3]
	v_mfma_f32_16x16x32_bf16 v[52:55], v[148:151], v[164:167], v[52:55]
	v_mfma_f32_16x16x32_bf16 v[48:51], v[156:159], v[164:167], v[48:51]
	v_mfma_f32_16x16x32_bf16 v[36:39], v[148:151], v[172:175], v[36:39]
	v_mfma_f32_16x16x32_bf16 v[32:35], v[156:159], v[172:175], v[32:35]
	v_mfma_f32_16x16x32_bf16 v[20:23], v[148:151], v[182:185], v[20:23]
	v_mfma_f32_16x16x32_bf16 v[16:19], v[156:159], v[182:185], v[16:19]
	v_mfma_f32_16x16x32_bf16 v[4:7], v[148:151], v[190:193], v[4:7]
	v_mfma_f32_16x16x32_bf16 v[0:3], v[156:159], v[190:193], v[0:3]
	s_barrier
	s_add_i32 s39, 0, 0x18000
	s_add_i32 s85, 0, 0x1c000
	v_add_u32_e32 v132, s39, v246
	v_add_u32_e32 v156, s85, v246
	ds_read_b128 v[104:107], v132
	ds_read_b128 v[112:115], v132 offset:1024
	ds_read_b128 v[124:127], v132 offset:2048
	ds_read_b128 v[132:135], v132 offset:3072
	ds_read_b128 v[144:147], v156
	ds_read_b128 v[148:151], v156 offset:1024
	ds_read_b128 v[152:155], v156 offset:2048
	ds_read_b128 v[156:159], v156 offset:3072
	s_add_u32 s8, s8, s22
	s_addc_u32 s9, s9, 0
	s_mov_b32 m0, s46
	v_lshl_add_u64 v[222:223], s[8:9], 0, v[206:207]
	ds_read_b128 v[160:163], v247 offset:32768
	ds_read_b128 v[164:167], v247 offset:33792
	ds_read_b128 v[168:171], v247 offset:34816
	ds_read_b128 v[172:175], v247 offset:35840
	ds_read_b128 v[178:181], v247 offset:36864
	ds_read_b128 v[182:185], v247 offset:37888
	ds_read_b128 v[186:189], v247 offset:38912
	ds_read_b128 v[190:193], v247 offset:39936
	global_load_lds_dwordx4 v[222:223], off
	v_lshl_add_u64 v[222:223], s[8:9], 0, v[204:205]
	s_mov_b32 m0, s47
	s_nop 0
	global_load_lds_dwordx4 v[222:223], off
	s_waitcnt vmcnt(8)
	s_waitcnt lgkmcnt(0)
	s_barrier
; #define PG8_STAGE(bufoff, gbase, voff) do { _Pragma("unroll") for (int _i = 0; _i < 2; ++_i) \
;         __builtin_amdgcn_global_load_lds((const unsigned*)((const char*)(gbase) + (voff)[_i]), (PG8_LAS unsigned*)(lds + (bufoff) + ldsw + _i * 8192), 16, 0, 0); } while (0)
; #define PG8_LDA(dst, b, h) do { _Pragma("unroll") for (int m = 0; m < 4; ++m) _Pragma("unroll") for (int k = 0; k < 2; ++k) dst[m][k] = *(const PG8_LAS bf16x8*)(lds + PG8_SA(b, h) + aoff + m * 2048 + k * 1024); } while (0)
; #define PG8_MMA(ai, bj, At, Bt) do { __builtin_amdgcn_s_setprio(1); _Pragma("unroll") for (int m = 0; m < 4; ++m) _Pragma("unroll") for (int n = 0; n < 2; ++n) _Pragma("unroll") for (int k = 0; k < 2; ++k) \
;         acc[ai][bj][m][n] = __builtin_amdgcn_mfma_f32_16x16x32_bf16(Bt[n][k], At[m][k], acc[ai][bj][m][n], 0, 0, 0); __builtin_amdgcn_s_setprio(0); } while (0)
; #define PG8_WAIT_V(n) asm volatile("s_waitcnt vmcnt(" #n ")" ::: "memory")
; #define PG8_WAIT_L(n) asm volatile("s_waitcnt lgkmcnt(" #n ")" ::: "memory")
; #define PG8_BAR __builtin_amdgcn_s_barrier()
; #define PG8_SCHED __builtin_amdgcn_sched_barrier(0)
; template <class Epi, class Sched, bool ALIGN_EPI = false, bool SP2 = false>
; __device__ __forceinline__ void gemm_phase(PG8_LAS unsigned char* lds, const Gemm g, const Sched& S, const Epi& E, const int wid_) {
;     ...
;             PG8_WAIT_V(8); PG8_WAIT_L(0); PG8_BAR; PG8_MMA(0, 0, At, B0); PG8_MMA(0, 1, At, B1); PG8_BAR; PG8_SCHED;
;             PG8_LDA(At, 1, 1); PG8_STAGE(PG8_SB(1, 0), b3, voffB); PG8_STAGE(PG8_SB(1, 1), b3 + hstepB, voffB); PG8_STAGE(PG8_SA(1, 0), a3, voffA);
;             PG8_WAIT_V(8); PG8_WAIT_L(0); PG8_BAR; PG8_MMA(1, 0, At, B0); PG8_MMA(1, 1, At, B1); PG8_BAR; PG8_SCHED;
	s_waitcnt lgkmcnt(0)
	v_mfma_f32_16x16x32_bf16 v[140:143], v[104:107], v[160:163], v[140:143]
	v_mfma_f32_16x16x32_bf16 v[136:139], v[124:127], v[160:163], v[136:139]
	v_mfma_f32_16x16x32_bf16 v[116:119], v[104:107], v[168:171], v[116:119]
	v_mfma_f32_16x16x32_bf16 v[108:111], v[124:127], v[168:171], v[108:111]
	v_mfma_f32_16x16x32_bf16 v[92:95], v[104:107], v[178:181], v[92:95]
	v_mfma_f32_16x16x32_bf16 v[88:91], v[124:127], v[178:181], v[88:91]
	v_mfma_f32_16x16x32_bf16 v[76:79], v[104:107], v[186:189], v[76:79]
	v_mfma_f32_16x16x32_bf16 v[72:75], v[124:127], v[186:189], v[72:75]
	v_mfma_f32_16x16x32_bf16 v[140:143], v[112:115], v[164:167], v[140:143]
	v_mfma_f32_16x16x32_bf16 v[136:139], v[132:135], v[164:167], v[136:139]
	v_mfma_f32_16x16x32_bf16 v[116:119], v[112:115], v[172:175], v[116:119]
	v_mfma_f32_16x16x32_bf16 v[108:111], v[132:135], v[172:175], v[108:111]
	v_mfma_f32_16x16x32_bf16 v[92:95], v[112:115], v[182:185], v[92:95]
	v_mfma_f32_16x16x32_bf16 v[88:91], v[132:135], v[182:185], v[88:91]
	v_mfma_f32_16x16x32_bf16 v[76:79], v[112:115], v[190:193], v[76:79]
	v_mfma_f32_16x16x32_bf16 v[72:75], v[132:135], v[190:193], v[72:75]
	v_mfma_f32_16x16x32_bf16 v[128:131], v[144:147], v[160:163], v[128:131]
	v_mfma_f32_16x16x32_bf16 v[120:123], v[152:155], v[160:163], v[120:123]
	v_mfma_f32_16x16x32_bf16 v[100:103], v[144:147], v[168:171], v[100:103]
	v_mfma_f32_16x16x32_bf16 v[96:99], v[152:155], v[168:171], v[96:99]
	v_mfma_f32_16x16x32_bf16 v[84:87], v[144:147], v[178:181], v[84:87]
	v_mfma_f32_16x16x32_bf16 v[80:83], v[152:155], v[178:181], v[80:83]
	v_mfma_f32_16x16x32_bf16 v[68:71], v[144:147], v[186:189], v[68:71]
	v_mfma_f32_16x16x32_bf16 v[64:67], v[152:155], v[186:189], v[64:67]
	v_mfma_f32_16x16x32_bf16 v[128:131], v[148:151], v[164:167], v[128:131]
	v_mfma_f32_16x16x32_bf16 v[120:123], v[156:159], v[164:167], v[120:123]
	v_mfma_f32_16x16x32_bf16 v[100:103], v[148:151], v[172:175], v[100:103]
	v_mfma_f32_16x16x32_bf16 v[96:99], v[156:159], v[172:175], v[96:99]
	v_mfma_f32_16x16x32_bf16 v[84:87], v[148:151], v[182:185], v[84:87]
	v_mfma_f32_16x16x32_bf16 v[80:83], v[156:159], v[182:185], v[80:83]
	v_mfma_f32_16x16x32_bf16 v[68:71], v[148:151], v[190:193], v[68:71]
	v_mfma_f32_16x16x32_bf16 v[64:67], v[156:159], v[190:193], v[64:67]
	s_barrier
	s_add_i32 s8, s39, s33
	v_lshl_add_u64 v[194:195], v[194:195], 0, s[66:67]
	s_mov_b32 m0, s8
	ds_read_b128 v[160:163], v247 offset:49152
	ds_read_b128 v[164:167], v247 offset:50176
	ds_read_b128 v[168:171], v247 offset:51200
	ds_read_b128 v[172:175], v247 offset:52224
	ds_read_b128 v[178:181], v247 offset:53248
	ds_read_b128 v[182:185], v247 offset:54272
	ds_read_b128 v[186:189], v247 offset:55296
	ds_read_b128 v[190:193], v247 offset:56320
	global_load_lds_dwordx4 v[194:195], off
	v_lshl_add_u64 v[194:195], v[196:197], 0, s[66:67]
	s_add_i32 m0, s8, 0x2000
	s_add_i32 s8, s85, s33
	global_load_lds_dwordx4 v[194:195], off
	v_lshl_add_u64 v[194:195], v[198:199], 0, s[66:67]
	s_mov_b32 m0, s8
	s_nop 0
	global_load_lds_dwordx4 v[194:195], off
	v_lshl_add_u64 v[194:195], v[200:201], 0, s[66:67]
	s_add_i32 m0, s8, 0x2000
	s_nop 0
	global_load_lds_dwordx4 v[194:195], off
	v_lshl_add_u64 v[194:195], v[218:219], 0, s[66:67]
	s_mov_b32 m0, s68
	s_nop 0
	global_load_lds_dwordx4 v[194:195], off
	v_lshl_add_u64 v[194:195], v[220:221], 0, s[66:67]
	s_mov_b32 m0, s69
	s_nop 0
	global_load_lds_dwordx4 v[194:195], off
	s_waitcnt vmcnt(8)
	s_waitcnt lgkmcnt(0)
	s_barrier
	s_waitcnt lgkmcnt(0)
	v_mfma_f32_16x16x32_bf16 v[60:63], v[104:107], v[160:163], v[60:63]
	v_mfma_f32_16x16x32_bf16 v[56:59], v[124:127], v[160:163], v[56:59]
	v_mfma_f32_16x16x32_bf16 v[44:47], v[104:107], v[168:171], v[44:47]
	v_mfma_f32_16x16x32_bf16 v[40:43], v[124:127], v[168:171], v[40:43]
	v_mfma_f32_16x16x32_bf16 v[28:31], v[104:107], v[178:181], v[28:31]
	v_mfma_f32_16x16x32_bf16 v[24:27], v[124:127], v[178:181], v[24:27]
	v_mfma_f32_16x16x32_bf16 v[12:15], v[104:107], v[186:189], v[12:15]
	v_mfma_f32_16x16x32_bf16 v[8:11], v[124:127], v[186:189], v[8:11]
	v_mfma_f32_16x16x32_bf16 v[60:63], v[112:115], v[164:167], v[60:63]
	v_mfma_f32_16x16x32_bf16 v[56:59], v[132:135], v[164:167], v[56:59]
	v_mfma_f32_16x16x32_bf16 v[44:47], v[112:115], v[172:175], v[44:47]
	v_mfma_f32_16x16x32_bf16 v[40:43], v[132:135], v[172:175], v[40:43]
	v_mfma_f32_16x16x32_bf16 v[28:31], v[112:115], v[182:185], v[28:31]
	v_mfma_f32_16x16x32_bf16 v[24:27], v[132:135], v[182:185], v[24:27]
	v_mfma_f32_16x16x32_bf16 v[12:15], v[112:115], v[190:193], v[12:15]
	v_mfma_f32_16x16x32_bf16 v[8:11], v[132:135], v[190:193], v[8:11]
	v_mfma_f32_16x16x32_bf16 v[52:55], v[144:147], v[160:163], v[52:55]
	v_mfma_f32_16x16x32_bf16 v[48:51], v[152:155], v[160:163], v[48:51]
	v_mfma_f32_16x16x32_bf16 v[36:39], v[144:147], v[168:171], v[36:39]
	v_mfma_f32_16x16x32_bf16 v[32:35], v[152:155], v[168:171], v[32:35]
	v_mfma_f32_16x16x32_bf16 v[20:23], v[144:147], v[178:181], v[20:23]
	v_mfma_f32_16x16x32_bf16 v[16:19], v[152:155], v[178:181], v[16:19]
	v_mfma_f32_16x16x32_bf16 v[4:7], v[144:147], v[186:189], v[4:7]
	v_mfma_f32_16x16x32_bf16 v[0:3], v[152:155], v[186:189], v[0:3]
	v_mfma_f32_16x16x32_bf16 v[52:55], v[148:151], v[164:167], v[52:55]
	v_mfma_f32_16x16x32_bf16 v[48:51], v[156:159], v[164:167], v[48:51]
	v_mfma_f32_16x16x32_bf16 v[36:39], v[148:151], v[172:175], v[36:39]
	v_mfma_f32_16x16x32_bf16 v[32:35], v[156:159], v[172:175], v[32:35]
	v_mfma_f32_16x16x32_bf16 v[20:23], v[148:151], v[182:185], v[20:23]
	v_mfma_f32_16x16x32_bf16 v[16:19], v[156:159], v[182:185], v[16:19]
	v_mfma_f32_16x16x32_bf16 v[4:7], v[148:151], v[190:193], v[4:7]
	v_mfma_f32_16x16x32_bf16 v[0:3], v[156:159], v[190:193], v[0:3]
	s_barrier
	s_add_u32 s11, s11, 0x100
	s_addc_u32 s76, s76, 0
	s_add_u32 s6, s6, 0x100
	s_addc_u32 s7, s7, 0
	s_cmp_ge_u32 s38, s71
	s_mov_b32 s8, s38
	s_cbranch_scc0 .LBB0_614
	s_setprio 0
	s_and_b64 vcc, exec, s[36:37]
	s_cbranch_vccz .LBB0_617
	s_barrier
